# delta step: beta folded into the stored v (be*v) and into the second gate scalar (be*a), so w = fma(-be*a, X, be*v) replaces fma+mul (one VALU slot less per step)
# speedup vs baseline: 1.0053x; 1.0053x over previous
; __device__ __forceinline__ float bflo(unsigned u) { return __uint_as_float(u << 16); }
; __device__ __forceinline__ float bfhi(unsigned u) { return __uint_as_float(u & 0xffff0000u); }
; template <int N, int RS>
; __device__ __forceinline__ void convN(const bf16_t* rawb, const float (&w)[4][N], int tt, int off, float (&x)[N]) {
; #pragma unroll
;   for (int i = 0; i < N; ++i) x[i] = 0.f;
; #pragma unroll
;   for (int j = 0; j < 4; ++j) {
;     float xv[N];
;     if (N == 8) { const uint4 rv = *(const uint4*)(rawb + (tt + j) * RS + off); unpack8(rv, xv); }
;     else if (N == 4) { const uint2 rv = *(const uint2*)(rawb + (tt + j) * RS + off); xv[0] = bflo(rv.x); xv[1] = bfhi(rv.x); xv[2 % N] = bflo(rv.y); xv[3 % N] = bfhi(rv.y); }
;     else { const unsigned rv = *(const unsigned*)(rawb + (tt + j) * RS + off); xv[0] = bflo(rv); xv[1] = bfhi(rv); }
; #pragma unroll
;     for (int i = 0; i < N; ++i) x[i] += w[j][i] * xv[i];
;   }
; template <int MIX>
; __device__ __forceinline__ void scan_part(const Params& p, const int layer, const int smp, const int b0, const int bstep, const int bend, const int h, const int part, char* lds, const int tid) {
;     ...
;       if (valid) {
;         float xq[8], xk[8], xv[VN];
;         { float cwv[4][VN];
; #pragma unroll
;           for (int j = 0; j < 4; ++j)
; #pragma unroll
;             for (int i = 0; i < VN; ++i) cwv[j][i] = cwl[j * RS + 128 + sub * VN + i];
;           convN<VN, RS>(rawb, cwv, tt, 128 + sub * VN, xv); }
;         convN<8, RS>(rawb, cwq, tt, sub * 8, xq);
;         convN<8, RS>(rawb, cwk, tt, 64 + sub * 8, xk);
.Ld_top_done:
	s_and_saveexec_b64 s[50:51], s[42:43]
	s_cbranch_execz .LBB0_426
	v_add_u32_e32 v232, s23, v131
	v_lshlrev_b32_e32 v232, 2, v232
	ds_read_b32 v230, v232 offset:50880
	v_lshlrev_b32_e32 v231, 16, v133
	v_mul_f32_e32 v231, 0xbfb8aa3b, v231
	ds_read_b128 v[78:81], v151 offset:37376
	ds_read_b128 v[82:85], v151 offset:37504
	ds_read_b128 v[86:89], v151 offset:37664
	ds_read_b128 v[90:93], v151 offset:37952
	ds_read_b128 v[174:177], v151 offset:38240
	v_add_u32_e32 v2, v140, v138
	v_add_u32_e32 v0, 0x9200, v2
	v_add_u32_e32 v216, 0xbc00, v137
	v_exp_f32_e32 v231, v231
	ds_read2_b32 v[0:1], v0 offset0:64 offset1:136
	ds_read2_b64 v[216:219], v216 offset0:120 offset1:192
	v_add_u32_e32 v220, 0xc000, v137
	v_add_u32_e32 v2, 0x9400, v2
	v_add_f32_e32 v231, 1.0, v231
	ds_read2_b64 v[220:223], v220 offset0:136 offset1:208
	s_waitcnt lgkmcnt(2)
	v_lshlrev_b32_e32 v225, 16, v1
	v_lshlrev_b32_e32 v224, 16, v0
	v_rcp_f32_e32 v231, v231
	s_waitcnt lgkmcnt(1)
	v_mov_b32_e32 v226, v216
	v_mov_b32_e32 v227, v218
	v_pk_mul_f32 v[224:225], v[226:227], v[224:225]
	v_and_b32_e32 v1, 0xffff0000, v1
	v_add_f32_e32 v216, 0, v224
	v_add_f32_e32 v226, v216, v225
	ds_read2_b32 v[224:225], v2 offset0:80 offset1:152
	v_and_b32_e32 v0, 0xffff0000, v0
	v_mov_b32_e32 v218, v217
	v_pk_mul_f32 v[0:1], v[218:219], v[0:1]
	s_waitcnt lgkmcnt(1)
	v_mov_b32_e32 v216, v220
	v_add_f32_e32 v0, 0, v0
	v_add_f32_e32 v2, v0, v1
	s_waitcnt lgkmcnt(0)
	v_lshlrev_b32_e32 v1, 16, v225
	v_lshlrev_b32_e32 v0, 16, v224
	v_mov_b32_e32 v217, v222
	v_pk_mul_f32 v[0:1], v[216:217], v[0:1]
	v_and_b32_e32 v217, 0xffff0000, v225
	v_and_b32_e32 v216, 0xffff0000, v224
	v_mov_b32_e32 v222, v221
	v_add_f32_e32 v0, v226, v0
	v_pk_mul_f32 v[216:217], v[222:223], v[216:217]
	v_add_f32_e32 v0, v0, v1
	v_add_f32_e32 v1, v2, v216
	v_add_f32_e32 v1, v1, v217
	v_mul_f32_e32 v2, 0xbfb8aa3b, v0
	v_exp_f32_e32 v2, v2
	v_mul_f32_e32 v76, 0xbfb8aa3b, v1
	v_exp_f32_e32 v77, v76
	s_waitcnt lgkmcnt(4)
	v_lshlrev_b32_e32 v154, 16, v80
	v_and_b32_e32 v155, 0xffff0000, v80
	v_lshlrev_b32_e32 v94, 16, v78
	v_and_b32_e32 v95, 0xffff0000, v78
	v_lshlrev_b32_e32 v106, 16, v79
	v_and_b32_e32 v107, 0xffff0000, v79
	v_lshlrev_b32_e32 v178, 16, v81
	v_and_b32_e32 v179, 0xffff0000, v81
	ds_read_b128 v[78:81], v151 offset:37792
	s_waitcnt lgkmcnt(3)
	v_lshlrev_b32_e32 v180, 16, v86
	v_and_b32_e32 v181, 0xffff0000, v86
	v_lshlrev_b32_e32 v182, 16, v87
	v_and_b32_e32 v183, 0xffff0000, v87
	v_lshlrev_b32_e32 v184, 16, v88
	v_and_b32_e32 v185, 0xffff0000, v88
	v_lshlrev_b32_e32 v186, 16, v89
	v_and_b32_e32 v187, 0xffff0000, v89
	ds_read_b128 v[86:89], v151 offset:38080
	s_waitcnt lgkmcnt(3)
	v_lshlrev_b32_e32 v188, 16, v90
	v_and_b32_e32 v189, 0xffff0000, v90
	v_lshlrev_b32_e32 v190, 16, v91
	v_and_b32_e32 v191, 0xffff0000, v91
	v_lshlrev_b32_e32 v192, 16, v92
	v_and_b32_e32 v193, 0xffff0000, v92
	v_lshlrev_b32_e32 v194, 16, v93
	v_and_b32_e32 v195, 0xffff0000, v93
	ds_read_b128 v[90:93], v151 offset:38368
	s_waitcnt vmcnt(2)
	v_pk_fma_f32 v[154:155], v[4:5], v[154:155], 0 op_sel_hi:[1,1,0]
	v_add_f32_e32 v2, 1.0, v2
	s_waitcnt vmcnt(2)
	v_pk_fma_f32 v[154:155], v[12:13], v[184:185], v[154:155]
	s_waitcnt lgkmcnt(3)
	v_lshlrev_b32_e32 v198, 16, v176
	v_and_b32_e32 v199, 0xffff0000, v176
	s_waitcnt vmcnt(2)
	v_pk_fma_f32 v[154:155], v[20:21], v[192:193], v[154:155]
	v_rcp_f32_e32 v76, v2
	v_add_f32_e32 v2, 1.0, v77
	s_waitcnt vmcnt(2)
	v_pk_fma_f32 v[154:155], v[28:29], v[198:199], v[154:155]
	v_rcp_f32_e32 v77, v2
	v_mul_f32_e32 v2, 0xbfb8aa3b, v154
	v_lshlrev_b32_e32 v202, 16, v84
	v_and_b32_e32 v203, 0xffff0000, v84
	s_waitcnt lgkmcnt(0)
	v_lshlrev_b32_e32 v214, 16, v92
	v_and_b32_e32 v215, 0xffff0000, v92
	v_exp_f32_e32 v2, v2
	v_mul_f32_e32 v92, 0xbfb8aa3b, v155
	v_lshlrev_b32_e32 v206, 16, v80
	v_and_b32_e32 v207, 0xffff0000, v80
	v_exp_f32_e32 v158, v92
	s_waitcnt vmcnt(2)
	v_pk_fma_f32 v[192:193], v[36:37], v[202:203], 0 op_sel_hi:[1,1,0]
	v_lshlrev_b32_e32 v210, 16, v88
	v_and_b32_e32 v211, 0xffff0000, v88
	s_waitcnt vmcnt(2)
	v_pk_fma_f32 v[192:193], v[44:45], v[206:207], v[192:193]
	v_add_f32_e32 v2, 1.0, v2
	s_waitcnt vmcnt(2)
	v_pk_fma_f32 v[192:193], v[52:53], v[210:211], v[192:193]
	v_rcp_f32_e32 v184, v2
	s_waitcnt vmcnt(2)
; __device__ __forceinline__ float bflo(unsigned u) { return __uint_as_float(u << 16); }
; __device__ __forceinline__ float bfhi(unsigned u) { return __uint_as_float(u & 0xffff0000u); }
; __device__ __forceinline__ float siluf_(float x) { return x * __builtin_amdgcn_rcpf(1.0f + __expf(-x)); }
; template <int N, int RS>
; __device__ __forceinline__ void convN(const bf16_t* rawb, const float (&w)[4][N], int tt, int off, float (&x)[N]) {
; #pragma unroll
;   for (int i = 0; i < N; ++i) x[i] = 0.f;
; #pragma unroll
;   for (int j = 0; j < 4; ++j) {
;     float xv[N];
;     if (N == 8) { const uint4 rv = *(const uint4*)(rawb + (tt + j) * RS + off); unpack8(rv, xv); }
;     else if (N == 4) { const uint2 rv = *(const uint2*)(rawb + (tt + j) * RS + off); xv[0] = bflo(rv.x); xv[1] = bfhi(rv.x); xv[2 % N] = bflo(rv.y); xv[3 % N] = bfhi(rv.y); }
;     else { const unsigned rv = *(const unsigned*)(rawb + (tt + j) * RS + off); xv[0] = bflo(rv); xv[1] = bfhi(rv); }
; #pragma unroll
;     for (int i = 0; i < N; ++i) x[i] += w[j][i] * xv[i];
;   }
;   if (N == 2) {
; #pragma unroll
;     for (int i = 0; i < N; ++i) asm volatile("" : "+v"(x[i]));
;   }
; #pragma unroll
;   for (int i = 0; i < N; ++i) x[i] = siluf_(x[i]);
; }
	v_pk_fma_f32 v[192:193], v[60:61], v[214:215], v[192:193]
	v_add_f32_e32 v2, 1.0, v158
	v_mul_f32_e32 v158, 0xbfb8aa3b, v192
	v_exp_f32_e32 v158, v158
	v_mul_f32_e32 v159, 0xbfb8aa3b, v193
	v_exp_f32_e32 v159, v159
	v_pk_fma_f32 v[178:179], v[6:7], v[178:179], 0 op_sel_hi:[1,1,0]
	v_lshlrev_b32_e32 v176, 16, v177
	v_pk_fma_f32 v[178:179], v[14:15], v[186:187], v[178:179]
	v_and_b32_e32 v177, 0xffff0000, v177
	v_rcp_f32_e32 v185, v2
	v_add_f32_e32 v2, 1.0, v158
	v_pk_fma_f32 v[178:179], v[22:23], v[194:195], v[178:179]
	v_rcp_f32_e32 v198, v2
	v_add_f32_e32 v2, 1.0, v159
	v_pk_fma_f32 v[176:177], v[30:31], v[176:177], v[178:179]
	v_rcp_f32_e32 v199, v2
	v_mul_f32_e32 v2, 0xbfb8aa3b, v176
	v_exp_f32_e32 v2, v2
	v_mul_f32_e32 v158, 0xbfb8aa3b, v177
	v_exp_f32_e32 v158, v158
	v_pk_fma_f32 v[94:95], v[8:9], v[94:95], 0 op_sel_hi:[1,1,0]
	v_lshlrev_b32_e32 v196, 16, v174
	v_pk_fma_f32 v[94:95], v[16:17], v[180:181], v[94:95]
	v_and_b32_e32 v197, 0xffff0000, v174
	v_add_f32_e32 v2, 1.0, v2
	v_pk_fma_f32 v[94:95], v[24:25], v[188:189], v[94:95]
	v_rcp_f32_e32 v186, v2
	v_add_f32_e32 v2, 1.0, v158
	v_pk_fma_f32 v[94:95], v[32:33], v[196:197], v[94:95]
	v_rcp_f32_e32 v187, v2
	v_mul_f32_e32 v2, 0xbfb8aa3b, v94
	v_exp_f32_e32 v2, v2
	v_mul_f32_e32 v158, 0xbfb8aa3b, v95
	v_exp_f32_e32 v158, v158
	v_pk_fma_f32 v[106:107], v[10:11], v[106:107], 0 op_sel_hi:[1,1,0]
	v_lshlrev_b32_e32 v174, 16, v175
	v_pk_fma_f32 v[106:107], v[18:19], v[182:183], v[106:107]
	v_and_b32_e32 v175, 0xffff0000, v175
	v_pk_fma_f32 v[106:107], v[26:27], v[190:191], v[106:107]
	v_add_f32_e32 v2, 1.0, v2
	v_pk_fma_f32 v[106:107], v[34:35], v[174:175], v[106:107]
	v_rcp_f32_e32 v180, v2
	v_add_f32_e32 v2, 1.0, v158
	v_mul_f32_e32 v158, 0xbfb8aa3b, v106
	v_exp_f32_e32 v158, v158
	v_mul_f32_e32 v159, 0xbfb8aa3b, v107
	v_lshlrev_b32_e32 v84, 16, v85
	v_and_b32_e32 v85, 0xffff0000, v85
	v_exp_f32_e32 v159, v159
	v_lshlrev_b32_e32 v80, 16, v81
	v_and_b32_e32 v81, 0xffff0000, v81
	v_pk_fma_f32 v[84:85], v[38:39], v[84:85], 0 op_sel_hi:[1,1,0]
	v_lshlrev_b32_e32 v88, 16, v89
	v_and_b32_e32 v89, 0xffff0000, v89
	v_pk_fma_f32 v[80:81], v[46:47], v[80:81], v[84:85]
	v_lshlrev_b32_e32 v92, 16, v93
	v_and_b32_e32 v93, 0xffff0000, v93
	v_rcp_f32_e32 v181, v2
	v_add_f32_e32 v2, 1.0, v158
	v_pk_fma_f32 v[80:81], v[54:55], v[88:89], v[80:81]
	v_rcp_f32_e32 v174, v2
	v_add_f32_e32 v2, 1.0, v159
	v_pk_fma_f32 v[80:81], v[62:63], v[92:93], v[80:81]
	v_rcp_f32_e32 v175, v2
	v_mul_f32_e32 v2, 0xbfb8aa3b, v80
	v_exp_f32_e32 v2, v2
	v_mul_f32_e32 v84, 0xbfb8aa3b, v81
	v_exp_f32_e32 v89, v84
	v_lshlrev_b32_e32 v200, 16, v82
	v_and_b32_e32 v201, 0xffff0000, v82
	v_lshlrev_b32_e32 v204, 16, v78
	v_and_b32_e32 v205, 0xffff0000, v78
	v_add_f32_e32 v2, 1.0, v2
	v_pk_fma_f32 v[92:93], v[40:41], v[200:201], 0 op_sel_hi:[1,1,0]
	v_lshlrev_b32_e32 v82, 16, v83
	v_and_b32_e32 v83, 0xffff0000, v83
	v_lshlrev_b32_e32 v208, 16, v86
	v_and_b32_e32 v209, 0xffff0000, v86
	v_rcp_f32_e32 v88, v2
	v_add_f32_e32 v2, 1.0, v89
	v_pk_fma_f32 v[92:93], v[48:49], v[204:205], v[92:93]
	v_lshlrev_b32_e32 v78, 16, v79
	v_and_b32_e32 v79, 0xffff0000, v79
	v_lshlrev_b32_e32 v212, 16, v90
	v_and_b32_e32 v213, 0xffff0000, v90
	v_rcp_f32_e32 v89, v2
	v_pk_fma_f32 v[92:93], v[56:57], v[208:209], v[92:93]
	v_pk_fma_f32 v[82:83], v[42:43], v[82:83], 0 op_sel_hi:[1,1,0]
	v_lshlrev_b32_e32 v86, 16, v87
	v_and_b32_e32 v87, 0xffff0000, v87
	s_waitcnt vmcnt(2)
; __device__ __forceinline__ float bflo(unsigned u) { return __uint_as_float(u << 16); }
; __device__ __forceinline__ float sigmoidf_(float x) { return __builtin_amdgcn_rcpf(1.0f + __expf(-x)); }
; __device__ __forceinline__ float softplusf_(float x) { return fmaxf(x, 0.f) + __logf(1.0f + __expf(-fabsf(x))); }
; __device__ __forceinline__ float red8d(float x) { x += dpp_x1(x); x += dpp_x2(x); x += dpp_hm(x); return x; }
; template <int MIX>
; __device__ __forceinline__ void scan_part(const Params& p, const int layer, const int smp, const int b0, const int bstep, const int bend, const int h, const int part, char* lds, const int tid) {
;     ...
;         for (int i = 0; i < VN; ++i) dst[192 + sub * VN + i] = xv[i];
;         float ssq = 0.f, ssk = 0.f;
; #pragma unroll
;         for (int i = 0; i < 8; ++i) { ssq += xq[i] * xq[i]; ssk += xk[i] * xk[i]; }
;         ssq = red8d(ssq); ssk = red8d(ssk);
;         const float rq = rsqrtf(ssq + 1e-6f) * 0.125f, rk = rsqrtf(ssk + 1e-6f);
;         float qk = 0.f;
; #pragma unroll
;         for (int i = 0; i < 8; ++i) { xq[i] *= rq; xk[i] *= rk; qk += xq[i] * xk[i]; }
;         qk = red8d(qk);
;         *(f32x4*)(dst + sub * 8) = (f32x4){xq[0], xq[1], xq[2], xq[3]}; *(f32x4*)(dst + sub * 8 + 4) = (f32x4){xq[4], xq[5], xq[6], xq[7]};
;         *(f32x4*)(dst + 64 + sub * 8) = (f32x4){xk[0], xk[1], xk[2], xk[3]}; *(f32x4*)(dst + 64 + sub * 8 + 4) = (f32x4){xk[4], xk[5], xk[6], xk[7]};
;         if (sub == 0) {
;           const float be = sigmoidf_(bflo(ex0)), al = bflo(ex1);
;           const float a = __expf(-Aexp * softplusf_(al + dtb));
;           *(f32x4*)(scal + tt * 4) = (f32x4){a, be, qk, 0.f};
	v_pk_fma_f32 v[92:93], v[64:65], v[212:213], v[92:93]
	v_pk_fma_f32 v[78:79], v[50:51], v[78:79], v[82:83]
	v_lshlrev_b32_e32 v90, 16, v91
	v_and_b32_e32 v91, 0xffff0000, v91
	v_mul_f32_e32 v2, 0xbfb8aa3b, v92
	v_pk_fma_f32 v[78:79], v[58:59], v[86:87], v[78:79]
	v_exp_f32_e32 v2, v2
	v_mul_f32_e32 v158, 0xbfb8aa3b, v93
	v_pk_fma_f32 v[78:79], v[66:67], v[90:91], v[78:79]
	v_pk_mul_f32 v[106:107], v[106:107], v[174:175]
	v_exp_f32_e32 v158, v158
	v_pk_mul_f32 v[174:175], v[80:81], v[88:89]
	v_mul_f32_e32 v81, 0xbfb8aa3b, v78
	v_exp_f32_e32 v82, v81
	v_mul_f32_e32 v81, 0xbfb8aa3b, v79
	v_exp_f32_e32 v83, v81
	v_add_f32_e32 v2, 1.0, v2
	v_rcp_f32_e32 v80, v2
	v_add_f32_e32 v2, 1.0, v158
	v_rcp_f32_e32 v81, v2
	v_add_f32_e32 v2, 1.0, v82
	v_rcp_f32_e32 v82, v2
	v_add_f32_e32 v2, 1.0, v83
	v_rcp_f32_e32 v83, v2
	v_pk_mul_f32 v[94:95], v[94:95], v[180:181]
	v_pk_mul_f32 v[88:89], v[92:93], v[80:81]
	v_pk_mul_f32 v[180:181], v[94:95], v[94:95]
	v_pk_mul_f32 v[80:81], v[88:89], v[88:89]
	v_pk_mul_f32 v[90:91], v[78:79], v[82:83]
	v_pk_mul_f32 v[84:85], v[106:107], v[106:107]
	v_pk_mul_f32 v[78:79], v[90:91], v[90:91]
	v_mov_b32_e32 v82, v80
	v_mov_b32_e32 v83, v180
	v_mov_b32_e32 v180, v81
	v_pk_mul_f32 v[154:155], v[154:155], v[184:185]
	v_pk_mul_f32 v[192:193], v[192:193], v[198:199]
	v_pk_add_f32 v[80:81], v[82:83], v[180:181]
	v_mov_b32_e32 v82, v78
	v_mov_b32_e32 v83, v84
	v_pk_mul_f32 v[184:185], v[154:155], v[154:155]
	v_pk_mul_f32 v[178:179], v[192:193], v[192:193]
	v_pk_add_f32 v[80:81], v[80:81], v[82:83]
	v_mov_b32_e32 v84, v79
	v_pk_mul_f32 v[176:177], v[176:177], v[186:187]
	v_pk_add_f32 v[78:79], v[84:85], v[80:81]
	v_mov_b32_e32 v80, v178
	v_mov_b32_e32 v81, v184
	v_pk_mul_f32 v[182:183], v[176:177], v[176:177]
	v_pk_mul_f32 v[86:87], v[174:175], v[174:175]
	v_pk_add_f32 v[78:79], v[80:81], v[78:79]
	v_mov_b32_e32 v184, v179
	v_pk_add_f32 v[78:79], v[184:185], v[78:79]
	v_mov_b32_e32 v80, v86
	v_mov_b32_e32 v81, v182
	v_pk_add_f32 v[78:79], v[80:81], v[78:79]
	v_mov_b32_e32 v182, v87
	v_pk_add_f32 v[78:79], v[182:183], v[78:79]
	s_mov_b32 s44, 0x358637bd
	v_pk_mul_f32 v[0:1], v[0:1], v[76:77]
	v_mov_b32_dpp v81, v79 quad_perm:[1,0,3,2] row_mask:0xf bank_mask:0xf bound_ctrl:1
	v_mov_b32_dpp v80, v78 quad_perm:[1,0,3,2] row_mask:0xf bank_mask:0xf bound_ctrl:1
	v_pk_add_f32 v[78:79], v[78:79], v[80:81]
	v_pk_mul_f32 v[0:1], v[0:1], v[230:231] op_sel:[0,1]
	ds_write_b64 v141, v[0:1] offset:768
	s_nop 0
	v_mov_b32_dpp v81, v79 quad_perm:[2,3,0,1] row_mask:0xf bank_mask:0xf bound_ctrl:1
	v_mov_b32_dpp v80, v78 quad_perm:[2,3,0,1] row_mask:0xf bank_mask:0xf bound_ctrl:1
	v_pk_add_f32 v[78:79], v[78:79], v[80:81]
	s_nop 1
	v_mov_b32_dpp v81, v79 row_half_mirror row_mask:0xf bank_mask:0xf bound_ctrl:1
	v_mov_b32_dpp v80, v78 row_half_mirror row_mask:0xf bank_mask:0xf bound_ctrl:1
	v_pk_add_f32 v[78:79], v[78:79], v[80:81]
	s_nop 0
	v_pk_add_f32 v[78:79], v[78:79], s[44:45] op_sel_hi:[1,0]
	s_nop 0
	v_mul_f32_e32 v2, 0x4b800000, v79
	v_cmp_gt_f32_e32 vcc, s92, v79
	s_nop 1
	v_cndmask_b32_e32 v2, v79, v2, vcc
	v_rsq_f32_e32 v2, v2
	s_nop 0
	v_mul_f32_e32 v0, 0x45800000, v2
	v_cndmask_b32_e32 v0, v2, v0, vcc
	v_mul_f32_e32 v0, 0x3e000000, v0
	v_pk_mul_f32 v[76:77], v[94:95], v[0:1] op_sel_hi:[1,0]
	v_mul_f32_e32 v1, 0x4b800000, v78
	v_cmp_gt_f32_e32 vcc, s92, v78
	s_nop 1
	v_cndmask_b32_e32 v1, v78, v1, vcc
	v_rsq_f32_e32 v1, v1
	s_nop 0
	v_pk_mul_f32 v[78:79], v[106:107], v[0:1] op_sel_hi:[1,0]
	v_pk_mul_f32 v[80:81], v[154:155], v[0:1] op_sel_hi:[1,0]
	v_pk_mul_f32 v[82:83], v[176:177], v[0:1] op_sel_hi:[1,0]
	v_mul_f32_e32 v0, 0x45800000, v1
	v_cndmask_b32_e32 v0, v1, v0, vcc
	v_pk_mul_f32 v[84:85], v[88:89], v[0:1] op_sel_hi:[1,0]
	s_nop 0
	v_pk_mul_f32 v[86:87], v[90:91], v[0:1] op_sel_hi:[1,0]
	s_nop 0
	v_pk_mul_f32 v[88:89], v[192:193], v[0:1] op_sel_hi:[1,0]
	s_nop 0
	v_pk_mul_f32 v[90:91], v[174:175], v[0:1] op_sel_hi:[1,0]
	ds_write_b128 v152, v[76:79]
	ds_write_b128 v152, v[80:83] offset:16
	ds_write_b128 v152, v[84:87] offset:256
	ds_write_b128 v152, v[88:91] offset:272
	s_and_b64 exec, exec, s[38:39]
	s_cbranch_execz .LBB0_426
	v_mov_b32_e32 v2, 0
	s_waitcnt lgkmcnt(5)
	v_mov_b32_e32 v0, v230
	v_mul_f32_e32 v1, v231, v230
	ds_write_b128 v142, v[0:3] offset:36864

; template <int KG> __device__ __forceinline__ float redKG(float x) { x = red8d(x); if (KG == 16) x += dpp_rm(x); return x; }
; template <int MIX, int KPL, int KG>
; __device__ __forceinline__ float do_step(const StepIn<MIX, KPL>& s, float (&S)[KPL], const float gam) {
;   if (MIX == 0) {
;     float kS0 = 0.f, kS1 = 0.f, qS0 = 0.f, qS1 = 0.f;
; #pragma unroll
;     for (int i = 0; i < KPL; i += 2) { kS0 += s.k[i] * S[i]; kS1 += s.k[i + 1] * S[i + 1]; qS0 += s.q[i] * S[i]; qS1 += s.q[i + 1] * S[i + 1]; }
;     const float kS = redKG<KG>(kS0 + kS1), qS = redKG<KG>(qS0 + qS1);
;     const float w = s.be * (s.v - s.a * kS);
; #pragma unroll
;     for (int i = 0; i < KPL; ++i) S[i] = s.a * S[i] + s.k[i] * w;
;     return s.a * qS + s.qk * w;
; template <int MIX>
; __device__ __forceinline__ void scan_part(const Params& p, const int layer, const int smp, const int b0, const int bstep, const int bend, const int h, const int part, char* lds, const int tid) {
;     ...
;       for (int t = 0; t < ntok; t += 2) {
;         load_step<MIX, KPL>(qkdv, scal, t + 1, kg, col, sb);
;         __builtin_amdgcn_sched_barrier(0);
;         const float oa = do_step<MIX, KPL, KG>(sa, S, gam);
;         osave = (kg == (t & (KG - 1))) ? oa : osave;
;         load_step<MIX, KPL>(qkdv, scal, min(t + 2, ntok - 1), kg, col, sa);
;         __builtin_amdgcn_sched_barrier(0);
;         const float ob = do_step<MIX, KPL, KG>(sb, S, gam);
;         osave = (kg == ((t + 1) & (KG - 1))) ? ob : osave;
;         if (((t + 2) & (KG - 1)) == 0) obuf[(t + 2 - KG + kg) * CW + col] = osave;
;       }
.Lscan0p_blk:
	s_waitcnt lgkmcnt(4)
	v_pk_mul_f32 v[192:193], v[92:93], v[104:105]
	v_pk_fma_f32 v[192:193], v[94:95], v[102:103], v[192:193]
	v_add_f32_e32 v203, v192, v193
	v_pk_mul_f32 v[194:195], v[104:105], v[106:107] op_sel_hi:[1,0]
	v_pk_mul_f32 v[196:197], v[102:103], v[106:107] op_sel_hi:[1,0]
	v_add_f32_dpp v203, v203, v203 quad_perm:[1,0,3,2] row_mask:0xf bank_mask:0xf bound_ctrl:1
	ds_read_b128 v[178:181], v211 offset:2304
	ds_read_b64 v[158:159], v213 offset:36896
	v_add_f32_dpp v203, v203, v203 quad_perm:[2,3,0,1] row_mask:0xf bank_mask:0xf bound_ctrl:1
	ds_read_b32 v189, v212 offset:2816
	ds_read_b128 v[184:187], v211 offset:3328
	v_add_f32_dpp v203, v203, v203 row_half_mirror row_mask:0xf bank_mask:0xf bound_ctrl:1
	ds_read_b64 v[168:169], v213 offset:36912
	ds_read_b32 v190, v212 offset:3840
	v_add_f32_dpp v203, v203, v203 row_mirror row_mask:0xf bank_mask:0xf bound_ctrl:1
	v_fma_f32 v206, -v107, v203, v182
	v_pk_fma_f32 v[104:105], v[92:93], v[206:207], v[194:195] op_sel_hi:[1,0,1]
	v_pk_fma_f32 v[102:103], v[94:95], v[206:207], v[196:197] op_sel_hi:[1,0,1]
	s_waitcnt lgkmcnt(4)
	v_pk_mul_f32 v[192:193], v[174:175], v[104:105]
	v_pk_fma_f32 v[192:193], v[176:177], v[102:103], v[192:193]
	v_add_f32_e32 v203, v192, v193
	v_pk_mul_f32 v[198:199], v[76:77], v[104:105]
	v_pk_mul_f32 v[194:195], v[104:105], v[154:155] op_sel_hi:[1,0]
	v_add_f32_dpp v203, v203, v203 quad_perm:[1,0,3,2] row_mask:0xf bank_mask:0xf bound_ctrl:1
	v_pk_fma_f32 v[198:199], v[78:79], v[102:103], v[198:199]
	v_pk_mul_f32 v[196:197], v[102:103], v[154:155] op_sel_hi:[1,0]
	v_add_f32_dpp v203, v203, v203 quad_perm:[2,3,0,1] row_mask:0xf bank_mask:0xf bound_ctrl:1
	ds_read_b128 v[84:87], v211 offset:2048
	ds_read_b128 v[92:95], v211 offset:4352
	v_add_f32_dpp v203, v203, v203 row_half_mirror row_mask:0xf bank_mask:0xf bound_ctrl:1
	v_add_f32_e32 v215, v198, v199
	ds_read_b64 v[106:107], v213 offset:36928
	v_add_f32_dpp v203, v203, v203 row_mirror row_mask:0xf bank_mask:0xf bound_ctrl:1
	v_fma_f32 v206, -v155, v203, v188
	v_pk_fma_f32 v[104:105], v[174:175], v[206:207], v[194:195] op_sel_hi:[1,0,1]
	v_pk_fma_f32 v[102:103], v[176:177], v[206:207], v[196:197] op_sel_hi:[1,0,1]
	v_pk_mul_f32 v[192:193], v[178:179], v[104:105]
	v_pk_fma_f32 v[192:193], v[180:181], v[102:103], v[192:193]
	v_add_f32_e32 v203, v192, v193
	v_pk_mul_f32 v[200:201], v[80:81], v[104:105]
	v_pk_mul_f32 v[194:195], v[104:105], v[158:159] op_sel_hi:[1,0]
	v_add_f32_dpp v203, v203, v203 quad_perm:[1,0,3,2] row_mask:0xf bank_mask:0xf bound_ctrl:1
	v_pk_fma_f32 v[200:201], v[82:83], v[102:103], v[200:201]
	v_pk_mul_f32 v[196:197], v[102:103], v[158:159] op_sel_hi:[1,0]
	v_add_f32_dpp v203, v203, v203 quad_perm:[2,3,0,1] row_mask:0xf bank_mask:0xf bound_ctrl:1
	ds_read_b32 v182, v212 offset:4864
	ds_read_b128 v[88:91], v211 offset:3072
	v_add_f32_dpp v203, v203, v203 row_half_mirror row_mask:0xf bank_mask:0xf bound_ctrl:1
	ds_read_b128 v[174:177], v211 offset:5376
	v_add_f32_e32 v216, v200, v201
	v_add_f32_dpp v203, v203, v203 row_mirror row_mask:0xf bank_mask:0xf bound_ctrl:1
	s_waitcnt lgkmcnt(3)
	v_fma_f32 v206, -v159, v203, v189
	v_pk_fma_f32 v[104:105], v[178:179], v[206:207], v[194:195] op_sel_hi:[1,0,1]
	v_pk_fma_f32 v[102:103], v[180:181], v[206:207], v[196:197] op_sel_hi:[1,0,1]
	v_pk_mul_f32 v[192:193], v[184:185], v[104:105]
	v_pk_fma_f32 v[192:193], v[186:187], v[102:103], v[192:193]
	v_add_f32_e32 v203, v192, v193
	v_pk_mul_f32 v[198:199], v[84:85], v[104:105]
	v_pk_mul_f32 v[194:195], v[104:105], v[168:169] op_sel_hi:[1,0]
	v_add_f32_dpp v203, v203, v203 quad_perm:[1,0,3,2] row_mask:0xf bank_mask:0xf bound_ctrl:1
	v_pk_fma_f32 v[198:199], v[86:87], v[102:103], v[198:199]
	v_pk_mul_f32 v[196:197], v[102:103], v[168:169] op_sel_hi:[1,0]
	v_add_f32_dpp v203, v203, v203 quad_perm:[2,3,0,1] row_mask:0xf bank_mask:0xf bound_ctrl:1
	ds_read_b64 v[154:155], v213 offset:36944
	ds_read_b32 v188, v212 offset:5888
	v_add_f32_dpp v203, v203, v203 row_half_mirror row_mask:0xf bank_mask:0xf bound_ctrl:1
	ds_read_b128 v[76:79], v211 offset:4096
	ds_read_b128 v[178:181], v211 offset:6400
	v_add_f32_dpp v203, v203, v203 row_mirror row_mask:0xf bank_mask:0xf bound_ctrl:1
	v_fma_f32 v206, -v169, v203, v190
	v_pk_fma_f32 v[104:105], v[184:185], v[206:207], v[194:195] op_sel_hi:[1,0,1]
	v_pk_fma_f32 v[102:103], v[186:187], v[206:207], v[196:197] op_sel_hi:[1,0,1]
	v_pk_mul_f32 v[192:193], v[92:93], v[104:105]
	v_pk_fma_f32 v[192:193], v[94:95], v[102:103], v[192:193]
	v_add_f32_e32 v203, v192, v193
	s_waitcnt lgkmcnt(2)
	v_pk_mul_f32 v[200:201], v[88:89], v[104:105]
	v_pk_mul_f32 v[194:195], v[104:105], v[106:107] op_sel_hi:[1,0]
	v_add_f32_dpp v203, v203, v203 quad_perm:[1,0,3,2] row_mask:0xf bank_mask:0xf bound_ctrl:1
	v_pk_fma_f32 v[200:201], v[90:91], v[102:103], v[200:201]
	v_pk_mul_f32 v[196:197], v[102:103], v[106:107] op_sel_hi:[1,0]
	v_add_f32_dpp v203, v203, v203 quad_perm:[2,3,0,1] row_mask:0xf bank_mask:0xf bound_ctrl:1
	v_add_f32_e32 v217, v198, v199
	ds_read_b64 v[158:159], v213 offset:36960
	v_add_f32_dpp v203, v203, v203 row_half_mirror row_mask:0xf bank_mask:0xf bound_ctrl:1
	ds_read_b32 v189, v212 offset:6912
	ds_read_b128 v[80:83], v211 offset:5120
	v_add_f32_dpp v203, v203, v203 row_mirror row_mask:0xf bank_mask:0xf bound_ctrl:1
	v_fma_f32 v206, -v107, v203, v182
	v_pk_fma_f32 v[104:105], v[92:93], v[206:207], v[194:195] op_sel_hi:[1,0,1]
	v_pk_fma_f32 v[102:103], v[94:95], v[206:207], v[196:197] op_sel_hi:[1,0,1]
	v_pk_mul_f32 v[192:193], v[174:175], v[104:105]
	v_pk_fma_f32 v[192:193], v[176:177], v[102:103], v[192:193]
	v_add_f32_e32 v203, v192, v193
	s_waitcnt lgkmcnt(2)
; template <int KG> __device__ __forceinline__ float redKG(float x) { x = red8d(x); if (KG == 16) x += dpp_rm(x); return x; }
; template <int MIX, int KPL, int KG>
; __device__ __forceinline__ float do_step(const StepIn<MIX, KPL>& s, float (&S)[KPL], const float gam) {
;   if (MIX == 0) {
;     float kS0 = 0.f, kS1 = 0.f, qS0 = 0.f, qS1 = 0.f;
; #pragma unroll
;     for (int i = 0; i < KPL; i += 2) { kS0 += s.k[i] * S[i]; kS1 += s.k[i + 1] * S[i + 1]; qS0 += s.q[i] * S[i]; qS1 += s.q[i + 1] * S[i + 1]; }
;     const float kS = redKG<KG>(kS0 + kS1), qS = redKG<KG>(qS0 + qS1);
;     const float w = s.be * (s.v - s.a * kS);
; #pragma unroll
;     for (int i = 0; i < KPL; ++i) S[i] = s.a * S[i] + s.k[i] * w;
;     return s.a * qS + s.qk * w;
; template <int MIX>
; __device__ __forceinline__ void scan_part(const Params& p, const int layer, const int smp, const int b0, const int bstep, const int bend, const int h, const int part, char* lds, const int tid) {
;     ...
;       for (int t = 0; t < ntok; t += 2) {
;         load_step<MIX, KPL>(qkdv, scal, t + 1, kg, col, sb);
;         __builtin_amdgcn_sched_barrier(0);
;         const float oa = do_step<MIX, KPL, KG>(sa, S, gam);
;         osave = (kg == (t & (KG - 1))) ? oa : osave;
;         load_step<MIX, KPL>(qkdv, scal, min(t + 2, ntok - 1), kg, col, sa);
;         __builtin_amdgcn_sched_barrier(0);
;         const float ob = do_step<MIX, KPL, KG>(sb, S, gam);
;         osave = (kg == ((t + 1) & (KG - 1))) ? ob : osave;
;         if (((t + 2) & (KG - 1)) == 0) obuf[(t + 2 - KG + kg) * CW + col] = osave;
;       }
	v_pk_mul_f32 v[198:199], v[76:77], v[104:105]
	v_pk_mul_f32 v[194:195], v[104:105], v[154:155] op_sel_hi:[1,0]
	v_add_f32_dpp v203, v203, v203 quad_perm:[1,0,3,2] row_mask:0xf bank_mask:0xf bound_ctrl:1
	v_pk_fma_f32 v[198:199], v[78:79], v[102:103], v[198:199]
	v_pk_mul_f32 v[196:197], v[102:103], v[154:155] op_sel_hi:[1,0]
	v_add_f32_dpp v203, v203, v203 quad_perm:[2,3,0,1] row_mask:0xf bank_mask:0xf bound_ctrl:1
	ds_read_b128 v[184:187], v211 offset:7424
	v_add_f32_e32 v218, v200, v201
	v_add_f32_dpp v203, v203, v203 row_half_mirror row_mask:0xf bank_mask:0xf bound_ctrl:1
	ds_read_b64 v[168:169], v213 offset:36976
	ds_read_b32 v190, v212 offset:7936
	v_add_f32_dpp v203, v203, v203 row_mirror row_mask:0xf bank_mask:0xf bound_ctrl:1
	v_fma_f32 v206, -v155, v203, v188
	v_pk_fma_f32 v[104:105], v[174:175], v[206:207], v[194:195] op_sel_hi:[1,0,1]
	v_pk_fma_f32 v[102:103], v[176:177], v[206:207], v[196:197] op_sel_hi:[1,0,1]
	v_pk_mul_f32 v[192:193], v[178:179], v[104:105]
	v_pk_fma_f32 v[192:193], v[180:181], v[102:103], v[192:193]
	v_add_f32_e32 v203, v192, v193
	s_waitcnt lgkmcnt(2)
	v_pk_mul_f32 v[200:201], v[80:81], v[104:105]
	v_pk_mul_f32 v[194:195], v[104:105], v[158:159] op_sel_hi:[1,0]
	v_add_f32_dpp v203, v203, v203 quad_perm:[1,0,3,2] row_mask:0xf bank_mask:0xf bound_ctrl:1
	v_pk_fma_f32 v[200:201], v[82:83], v[102:103], v[200:201]
	v_pk_mul_f32 v[196:197], v[102:103], v[158:159] op_sel_hi:[1,0]
	v_add_f32_dpp v203, v203, v203 quad_perm:[2,3,0,1] row_mask:0xf bank_mask:0xf bound_ctrl:1
	ds_read_b128 v[84:87], v211 offset:6144
	ds_read_b128 v[92:95], v211 offset:8448
	v_add_f32_dpp v203, v203, v203 row_half_mirror row_mask:0xf bank_mask:0xf bound_ctrl:1
	v_add_f32_e32 v219, v198, v199
	ds_read_b64 v[106:107], v213 offset:36992
	v_add_f32_dpp v203, v203, v203 row_mirror row_mask:0xf bank_mask:0xf bound_ctrl:1
	v_fma_f32 v206, -v159, v203, v189
	v_pk_fma_f32 v[104:105], v[178:179], v[206:207], v[194:195] op_sel_hi:[1,0,1]
	v_pk_fma_f32 v[102:103], v[180:181], v[206:207], v[196:197] op_sel_hi:[1,0,1]
	v_pk_mul_f32 v[192:193], v[184:185], v[104:105]
	v_pk_fma_f32 v[192:193], v[186:187], v[102:103], v[192:193]
	v_add_f32_e32 v203, v192, v193
	s_waitcnt lgkmcnt(1)
	v_pk_mul_f32 v[194:195], v[104:105], v[168:169] op_sel_hi:[1,0]
	v_pk_mul_f32 v[198:199], v[84:85], v[104:105]
	v_add_f32_dpp v203, v203, v203 quad_perm:[1,0,3,2] row_mask:0xf bank_mask:0xf bound_ctrl:1
	v_pk_fma_f32 v[198:199], v[86:87], v[102:103], v[198:199]
	v_pk_mul_f32 v[196:197], v[102:103], v[168:169] op_sel_hi:[1,0]
	v_add_f32_dpp v203, v203, v203 quad_perm:[2,3,0,1] row_mask:0xf bank_mask:0xf bound_ctrl:1
	ds_read_b32 v182, v212 offset:8960
	ds_read_b128 v[88:91], v211 offset:7168
	v_add_f32_dpp v203, v203, v203 row_half_mirror row_mask:0xf bank_mask:0xf bound_ctrl:1
	ds_read_b128 v[174:177], v211 offset:9472
	v_add_f32_e32 v220, v200, v201
	v_add_f32_dpp v203, v203, v203 row_mirror row_mask:0xf bank_mask:0xf bound_ctrl:1
	v_fma_f32 v206, -v169, v203, v190
	v_pk_fma_f32 v[104:105], v[184:185], v[206:207], v[194:195] op_sel_hi:[1,0,1]
	v_pk_fma_f32 v[102:103], v[186:187], v[206:207], v[196:197] op_sel_hi:[1,0,1]
	v_pk_mul_f32 v[192:193], v[92:93], v[104:105]
	v_pk_fma_f32 v[192:193], v[94:95], v[102:103], v[192:193]
	v_add_f32_e32 v203, v192, v193
	s_waitcnt lgkmcnt(1)
	v_pk_mul_f32 v[194:195], v[104:105], v[106:107] op_sel_hi:[1,0]
	v_pk_mul_f32 v[196:197], v[102:103], v[106:107] op_sel_hi:[1,0]
	v_add_f32_dpp v203, v203, v203 quad_perm:[1,0,3,2] row_mask:0xf bank_mask:0xf bound_ctrl:1
	v_pk_mul_f32 v[200:201], v[88:89], v[104:105]
	v_pk_fma_f32 v[200:201], v[90:91], v[102:103], v[200:201]
	v_add_f32_dpp v203, v203, v203 quad_perm:[2,3,0,1] row_mask:0xf bank_mask:0xf bound_ctrl:1
	ds_read_b64 v[154:155], v213 offset:37008
	ds_read_b32 v188, v212 offset:9984
	v_add_f32_dpp v203, v203, v203 row_half_mirror row_mask:0xf bank_mask:0xf bound_ctrl:1
	ds_read_b128 v[76:79], v211 offset:8192
	ds_read_b128 v[178:181], v211 offset:10496
	v_add_f32_dpp v203, v203, v203 row_mirror row_mask:0xf bank_mask:0xf bound_ctrl:1
	v_fma_f32 v206, -v107, v203, v182
	v_pk_fma_f32 v[104:105], v[92:93], v[206:207], v[194:195] op_sel_hi:[1,0,1]
	v_pk_fma_f32 v[102:103], v[94:95], v[206:207], v[196:197] op_sel_hi:[1,0,1]
	s_waitcnt lgkmcnt(4)
	v_pk_mul_f32 v[192:193], v[174:175], v[104:105]
	v_pk_fma_f32 v[192:193], v[176:177], v[102:103], v[192:193]
	v_add_f32_e32 v203, v192, v193
	v_add_f32_e32 v221, v198, v199
	s_waitcnt lgkmcnt(1)
	v_pk_mul_f32 v[194:195], v[104:105], v[154:155] op_sel_hi:[1,0]
	v_add_f32_dpp v203, v203, v203 quad_perm:[1,0,3,2] row_mask:0xf bank_mask:0xf bound_ctrl:1
	v_pk_mul_f32 v[196:197], v[102:103], v[154:155] op_sel_hi:[1,0]
	v_pk_mul_f32 v[198:199], v[76:77], v[104:105]
	v_add_f32_dpp v203, v203, v203 quad_perm:[2,3,0,1] row_mask:0xf bank_mask:0xf bound_ctrl:1
	v_pk_fma_f32 v[198:199], v[78:79], v[102:103], v[198:199]
	ds_read_b64 v[158:159], v213 offset:37024
	v_add_f32_dpp v203, v203, v203 row_half_mirror row_mask:0xf bank_mask:0xf bound_ctrl:1
	ds_read_b32 v189, v212 offset:11008
	ds_read_b128 v[80:83], v211 offset:9216
	v_add_f32_dpp v203, v203, v203 row_mirror row_mask:0xf bank_mask:0xf bound_ctrl:1
	v_fma_f32 v206, -v155, v203, v188
	v_pk_fma_f32 v[104:105], v[174:175], v[206:207], v[194:195] op_sel_hi:[1,0,1]
	v_pk_fma_f32 v[102:103], v[176:177], v[206:207], v[196:197] op_sel_hi:[1,0,1]
	s_waitcnt lgkmcnt(3)
	v_pk_mul_f32 v[192:193], v[178:179], v[104:105]
	v_pk_fma_f32 v[192:193], v[180:181], v[102:103], v[192:193]
	v_add_f32_e32 v203, v192, v193
	ds_read_b128 v[184:187], v211 offset:11520
	v_add_f32_e32 v222, v200, v201
	v_add_f32_dpp v203, v203, v203 quad_perm:[1,0,3,2] row_mask:0xf bank_mask:0xf bound_ctrl:1
	s_waitcnt lgkmcnt(1)
; template <int KG> __device__ __forceinline__ float redKG(float x) { x = red8d(x); if (KG == 16) x += dpp_rm(x); return x; }
; template <int MIX, int KPL, int KG>
; __device__ __forceinline__ float do_step(const StepIn<MIX, KPL>& s, float (&S)[KPL], const float gam) {
;   if (MIX == 0) {
;     float kS0 = 0.f, kS1 = 0.f, qS0 = 0.f, qS1 = 0.f;
; #pragma unroll
;     for (int i = 0; i < KPL; i += 2) { kS0 += s.k[i] * S[i]; kS1 += s.k[i + 1] * S[i + 1]; qS0 += s.q[i] * S[i]; qS1 += s.q[i + 1] * S[i + 1]; }
;     const float kS = redKG<KG>(kS0 + kS1), qS = redKG<KG>(qS0 + qS1);
;     const float w = s.be * (s.v - s.a * kS);
; #pragma unroll
;     for (int i = 0; i < KPL; ++i) S[i] = s.a * S[i] + s.k[i] * w;
;     return s.a * qS + s.qk * w;
; template <int MIX>
; __device__ __forceinline__ void scan_part(const Params& p, const int layer, const int smp, const int b0, const int bstep, const int bend, const int h, const int part, char* lds, const int tid) {
;     ...
;       for (int t = 0; t < ntok; t += 2) {
;         load_step<MIX, KPL>(qkdv, scal, t + 1, kg, col, sb);
;         __builtin_amdgcn_sched_barrier(0);
;         const float oa = do_step<MIX, KPL, KG>(sa, S, gam);
;         osave = (kg == (t & (KG - 1))) ? oa : osave;
;         load_step<MIX, KPL>(qkdv, scal, min(t + 2, ntok - 1), kg, col, sa);
;         __builtin_amdgcn_sched_barrier(0);
;         const float ob = do_step<MIX, KPL, KG>(sb, S, gam);
;         osave = (kg == ((t + 1) & (KG - 1))) ? ob : osave;
;         if (((t + 2) & (KG - 1)) == 0) obuf[(t + 2 - KG + kg) * CW + col] = osave;
;       }
	v_pk_mul_f32 v[194:195], v[104:105], v[158:159] op_sel_hi:[1,0]
	v_pk_mul_f32 v[196:197], v[102:103], v[158:159] op_sel_hi:[1,0]
	v_add_f32_dpp v203, v203, v203 quad_perm:[2,3,0,1] row_mask:0xf bank_mask:0xf bound_ctrl:1
	v_pk_mul_f32 v[200:201], v[80:81], v[104:105]
	v_pk_fma_f32 v[200:201], v[82:83], v[102:103], v[200:201]
	v_add_f32_dpp v203, v203, v203 row_half_mirror row_mask:0xf bank_mask:0xf bound_ctrl:1
	ds_read_b64 v[168:169], v213 offset:37040
	ds_read_b32 v190, v212 offset:12032
	v_add_f32_dpp v203, v203, v203 row_mirror row_mask:0xf bank_mask:0xf bound_ctrl:1
	v_fma_f32 v206, -v159, v203, v189
	v_pk_fma_f32 v[104:105], v[178:179], v[206:207], v[194:195] op_sel_hi:[1,0,1]
	v_pk_fma_f32 v[102:103], v[180:181], v[206:207], v[196:197] op_sel_hi:[1,0,1]
	s_waitcnt lgkmcnt(2)
	v_pk_mul_f32 v[192:193], v[184:185], v[104:105]
	v_pk_fma_f32 v[192:193], v[186:187], v[102:103], v[192:193]
	ds_read_b128 v[84:87], v211 offset:10240
	v_add_f32_e32 v203, v192, v193
	ds_read_b128 v[92:95], v211 offset:12544
	v_cndmask_b32_e64 v223, v215, v216, s[52:53]
	v_add_f32_dpp v203, v203, v203 quad_perm:[1,0,3,2] row_mask:0xf bank_mask:0xf bound_ctrl:1
	v_cndmask_b32_e64 v224, v216, v215, s[52:53]
	v_add_f32_e32 v215, v198, v199
	v_add_f32_dpp v203, v203, v203 quad_perm:[2,3,0,1] row_mask:0xf bank_mask:0xf bound_ctrl:1
	s_waitcnt lgkmcnt(2)
	v_pk_mul_f32 v[194:195], v[104:105], v[168:169] op_sel_hi:[1,0]
	v_pk_mul_f32 v[196:197], v[102:103], v[168:169] op_sel_hi:[1,0]
	v_add_f32_dpp v203, v203, v203 row_half_mirror row_mask:0xf bank_mask:0xf bound_ctrl:1
	ds_read_b64 v[106:107], v213 offset:37056
	ds_read_b32 v182, v212 offset:13056
	v_add_f32_dpp v203, v203, v203 row_mirror row_mask:0xf bank_mask:0xf bound_ctrl:1
	s_waitcnt lgkmcnt(2)
	v_pk_mul_f32 v[198:199], v[84:85], v[104:105]
	v_fma_f32 v206, -v169, v203, v190
	v_pk_fma_f32 v[198:199], v[86:87], v[102:103], v[198:199]
	v_pk_fma_f32 v[104:105], v[184:185], v[206:207], v[194:195] op_sel_hi:[1,0,1]
	v_pk_fma_f32 v[102:103], v[186:187], v[206:207], v[196:197] op_sel_hi:[1,0,1]
	v_pk_mul_f32 v[192:193], v[92:93], v[104:105]
	v_pk_fma_f32 v[192:193], v[94:95], v[102:103], v[192:193]
	ds_read_b128 v[88:91], v211 offset:11264
	v_add_f32_e32 v203, v192, v193
	ds_read_b128 v[174:177], v211 offset:13568
	v_add_f32_e32 v216, v200, v201
	v_add_f32_dpp v203, v203, v203 quad_perm:[1,0,3,2] row_mask:0xf bank_mask:0xf bound_ctrl:1
	s_waitcnt lgkmcnt(2)
	v_pk_mul_f32 v[194:195], v[104:105], v[106:107] op_sel_hi:[1,0]
	v_pk_mul_f32 v[196:197], v[102:103], v[106:107] op_sel_hi:[1,0]
	v_add_f32_dpp v203, v203, v203 quad_perm:[2,3,0,1] row_mask:0xf bank_mask:0xf bound_ctrl:1
	ds_read_b64 v[154:155], v213 offset:37072
	ds_read_b32 v188, v212 offset:14080
	v_add_f32_dpp v203, v203, v203 row_half_mirror row_mask:0xf bank_mask:0xf bound_ctrl:1
	ds_read_b128 v[76:79], v211 offset:12288
	ds_read_b128 v[178:181], v211 offset:14592
	v_add_f32_dpp v203, v203, v203 row_mirror row_mask:0xf bank_mask:0xf bound_ctrl:1
	s_waitcnt lgkmcnt(4)
	v_pk_mul_f32 v[200:201], v[88:89], v[104:105]
	v_fma_f32 v206, -v107, v203, v182
	v_pk_fma_f32 v[200:201], v[90:91], v[102:103], v[200:201]
	v_pk_fma_f32 v[104:105], v[92:93], v[206:207], v[194:195] op_sel_hi:[1,0,1]
	v_pk_fma_f32 v[102:103], v[94:95], v[206:207], v[196:197] op_sel_hi:[1,0,1]
	v_pk_mul_f32 v[192:193], v[174:175], v[104:105]
	v_pk_fma_f32 v[192:193], v[176:177], v[102:103], v[192:193]
	v_add_f32_e32 v203, v192, v193
	v_cndmask_b32_e64 v225, v217, v218, s[52:53]
	v_cndmask_b32_e64 v226, v218, v217, s[52:53]
	v_add_f32_dpp v203, v203, v203 quad_perm:[1,0,3,2] row_mask:0xf bank_mask:0xf bound_ctrl:1
	v_add_f32_e32 v217, v198, v199
	s_waitcnt lgkmcnt(0)
	v_pk_mul_f32 v[198:199], v[76:77], v[104:105]
	v_add_f32_dpp v203, v203, v203 quad_perm:[2,3,0,1] row_mask:0xf bank_mask:0xf bound_ctrl:1
	v_pk_mul_f32 v[194:195], v[104:105], v[154:155] op_sel_hi:[1,0]
	v_pk_fma_f32 v[198:199], v[78:79], v[102:103], v[198:199]
	v_add_f32_dpp v203, v203, v203 row_half_mirror row_mask:0xf bank_mask:0xf bound_ctrl:1
	v_pk_mul_f32 v[196:197], v[102:103], v[154:155] op_sel_hi:[1,0]
	v_add_f32_dpp v227, v224, v223 quad_perm:[1,0,3,2] row_mask:0xf bank_mask:0xf bound_ctrl:1
	v_add_f32_dpp v203, v203, v203 row_mirror row_mask:0xf bank_mask:0xf bound_ctrl:1
	v_fma_f32 v206, -v155, v203, v188
	v_pk_fma_f32 v[104:105], v[174:175], v[206:207], v[194:195] op_sel_hi:[1,0,1]
	v_add_f32_dpp v228, v226, v225 quad_perm:[1,0,3,2] row_mask:0xf bank_mask:0xf bound_ctrl:1
	v_pk_fma_f32 v[102:103], v[176:177], v[206:207], v[196:197] op_sel_hi:[1,0,1]
	v_pk_mul_f32 v[192:193], v[178:179], v[104:105]
	v_cndmask_b32_e64 v223, v227, v228, s[54:55]
	v_cndmask_b32_e64 v224, v228, v227, s[54:55]
	ds_read_b64 v[158:159], v213 offset:37088
	ds_read_b32 v189, v212 offset:15104
	v_pk_fma_f32 v[192:193], v[180:181], v[102:103], v[192:193]
	ds_read_b128 v[80:83], v211 offset:13312
	v_add_f32_e32 v203, v192, v193
	v_add_f32_dpp v225, v224, v223 quad_perm:[2,3,0,1] row_mask:0xf bank_mask:0xf bound_ctrl:1
	ds_read_b128 v[184:187], v211 offset:15616
	v_add_f32_dpp v203, v203, v203 quad_perm:[1,0,3,2] row_mask:0xf bank_mask:0xf bound_ctrl:1
	v_add_f32_dpp v226, v225, v225 row_ror:4 row_mask:0xf bank_mask:0xf bound_ctrl:1
	v_cndmask_b32_e64 v223, v219, v220, s[52:53]
	v_add_f32_dpp v203, v203, v203 quad_perm:[2,3,0,1] row_mask:0xf bank_mask:0xf bound_ctrl:1
	v_add_f32_dpp v205, v226, v226 row_ror:8 row_mask:0xf bank_mask:0xf bound_ctrl:1
	v_cndmask_b32_e64 v224, v220, v219, s[52:53]
	v_cndmask_b32_e64 v225, v221, v222, s[52:53]
	v_cndmask_b32_e64 v226, v222, v221, s[52:53]
	v_add_f32_dpp v203, v203, v203 row_half_mirror row_mask:0xf bank_mask:0xf bound_ctrl:1
	v_add_f32_dpp v227, v224, v223 quad_perm:[1,0,3,2] row_mask:0xf bank_mask:0xf bound_ctrl:1
	v_add_f32_dpp v228, v226, v225 quad_perm:[1,0,3,2] row_mask:0xf bank_mask:0xf bound_ctrl:1
	v_add_f32_dpp v203, v203, v203 row_mirror row_mask:0xf bank_mask:0xf bound_ctrl:1
	v_cndmask_b32_e64 v223, v227, v228, s[54:55]
	v_cndmask_b32_e64 v224, v228, v227, s[54:55]
	v_add_f32_e32 v218, v200, v201
	s_waitcnt lgkmcnt(0)
; template <int KG> __device__ __forceinline__ float redKG(float x) { x = red8d(x); if (KG == 16) x += dpp_rm(x); return x; }
; template <int MIX, int KPL, int KG>
; __device__ __forceinline__ float do_step(const StepIn<MIX, KPL>& s, float (&S)[KPL], const float gam) {
;   if (MIX == 0) {
;     float kS0 = 0.f, kS1 = 0.f, qS0 = 0.f, qS1 = 0.f;
; #pragma unroll
;     for (int i = 0; i < KPL; i += 2) { kS0 += s.k[i] * S[i]; kS1 += s.k[i + 1] * S[i + 1]; qS0 += s.q[i] * S[i]; qS1 += s.q[i + 1] * S[i + 1]; }
;     const float kS = redKG<KG>(kS0 + kS1), qS = redKG<KG>(qS0 + qS1);
;     const float w = s.be * (s.v - s.a * kS);
; #pragma unroll
;     for (int i = 0; i < KPL; ++i) S[i] = s.a * S[i] + s.k[i] * w;
;     return s.a * qS + s.qk * w;
; template <int MIX>
; __device__ __forceinline__ void scan_part(const Params& p, const int layer, const int smp, const int b0, const int bstep, const int bend, const int h, const int part, char* lds, const int tid) {
;     ...
;       for (int t = 0; t < ntok; t += 2) {
;         load_step<MIX, KPL>(qkdv, scal, t + 1, kg, col, sb);
;         __builtin_amdgcn_sched_barrier(0);
;         const float oa = do_step<MIX, KPL, KG>(sa, S, gam);
;         osave = (kg == (t & (KG - 1))) ? oa : osave;
;         load_step<MIX, KPL>(qkdv, scal, min(t + 2, ntok - 1), kg, col, sa);
;         __builtin_amdgcn_sched_barrier(0);
;         const float ob = do_step<MIX, KPL, KG>(sb, S, gam);
;         osave = (kg == ((t + 1) & (KG - 1))) ? ob : osave;
;         if (((t + 2) & (KG - 1)) == 0) obuf[(t + 2 - KG + kg) * CW + col] = osave;
;       }
	v_pk_mul_f32 v[200:201], v[80:81], v[104:105]
	v_pk_mul_f32 v[194:195], v[104:105], v[158:159] op_sel_hi:[1,0]
	v_fma_f32 v206, -v159, v203, v189
	v_pk_fma_f32 v[200:201], v[82:83], v[102:103], v[200:201]
	v_pk_mul_f32 v[196:197], v[102:103], v[158:159] op_sel_hi:[1,0]
	v_pk_fma_f32 v[104:105], v[178:179], v[206:207], v[194:195] op_sel_hi:[1,0,1]
	v_add_f32_dpp v225, v224, v223 quad_perm:[2,3,0,1] row_mask:0xf bank_mask:0xf bound_ctrl:1
	v_pk_fma_f32 v[102:103], v[180:181], v[206:207], v[196:197] op_sel_hi:[1,0,1]
	v_pk_mul_f32 v[192:193], v[184:185], v[104:105]
	ds_read_b64 v[168:169], v213 offset:37104
	ds_read_b32 v190, v212 offset:16128
	v_pk_fma_f32 v[192:193], v[186:187], v[102:103], v[192:193]
	ds_read_b128 v[84:87], v211 offset:14336
	v_add_f32_e32 v203, v192, v193
	v_add_f32_dpp v226, v225, v225 row_ror:4 row_mask:0xf bank_mask:0xf bound_ctrl:1
	ds_read_b128 v[88:91], v211 offset:15360
	v_add_f32_dpp v203, v203, v203 quad_perm:[1,0,3,2] row_mask:0xf bank_mask:0xf bound_ctrl:1
	v_add_f32_dpp v208, v226, v226 row_ror:8 row_mask:0xf bank_mask:0xf bound_ctrl:1
	v_cndmask_b32_e64 v223, v215, v216, s[52:53]
	v_cndmask_b32_e64 v224, v216, v215, s[52:53]
	v_cndmask_b32_e64 v225, v217, v218, s[52:53]
	v_cndmask_b32_e64 v226, v218, v217, s[52:53]
	v_add_f32_dpp v203, v203, v203 quad_perm:[2,3,0,1] row_mask:0xf bank_mask:0xf bound_ctrl:1
	v_add_f32_dpp v227, v224, v223 quad_perm:[1,0,3,2] row_mask:0xf bank_mask:0xf bound_ctrl:1
	v_add_f32_dpp v228, v226, v225 quad_perm:[1,0,3,2] row_mask:0xf bank_mask:0xf bound_ctrl:1
	v_cndmask_b32_e64 v223, v227, v228, s[54:55]
	v_cndmask_b32_e64 v224, v228, v227, s[54:55]
	v_add_f32_dpp v203, v203, v203 row_half_mirror row_mask:0xf bank_mask:0xf bound_ctrl:1
	v_add_f32_e32 v219, v198, v199
	v_add_f32_dpp v225, v224, v223 quad_perm:[2,3,0,1] row_mask:0xf bank_mask:0xf bound_ctrl:1
	v_add_f32_dpp v203, v203, v203 row_mirror row_mask:0xf bank_mask:0xf bound_ctrl:1
	s_waitcnt lgkmcnt(0)
	v_pk_mul_f32 v[198:199], v[84:85], v[104:105]
	v_pk_mul_f32 v[194:195], v[104:105], v[168:169] op_sel_hi:[1,0]
	v_fma_f32 v206, -v169, v203, v190
	v_add_f32_dpp v226, v225, v225 row_ror:4 row_mask:0xf bank_mask:0xf bound_ctrl:1
	v_add_f32_e32 v220, v200, v201
	v_pk_fma_f32 v[198:199], v[86:87], v[102:103], v[198:199]
	v_pk_mul_f32 v[196:197], v[102:103], v[168:169] op_sel_hi:[1,0]
	v_pk_fma_f32 v[104:105], v[184:185], v[206:207], v[194:195] op_sel_hi:[1,0,1]
	v_pk_fma_f32 v[102:103], v[186:187], v[206:207], v[196:197] op_sel_hi:[1,0,1]
	v_pk_mul_f32 v[200:201], v[88:89], v[104:105]
	v_pk_fma_f32 v[200:201], v[90:91], v[102:103], v[200:201]
	v_add_f32_dpp v209, v226, v226 row_ror:8 row_mask:0xf bank_mask:0xf bound_ctrl:1
	v_add_f32_e32 v221, v198, v199
	v_add_f32_e32 v222, v200, v201
	v_cndmask_b32_e64 v223, v219, v220, s[52:53]
	v_cndmask_b32_e64 v224, v220, v219, s[52:53]
	v_cndmask_b32_e64 v225, v221, v222, s[52:53]
	v_cndmask_b32_e64 v226, v222, v221, s[52:53]
	v_add_f32_dpp v227, v224, v223 quad_perm:[1,0,3,2] row_mask:0xf bank_mask:0xf bound_ctrl:1
	ds_read_b128 v[92:95], v211 offset:16640
	v_add_f32_dpp v228, v226, v225 quad_perm:[1,0,3,2] row_mask:0xf bank_mask:0xf bound_ctrl:1
	v_cndmask_b32_e64 v223, v227, v228, s[54:55]
	v_cndmask_b32_e64 v224, v228, v227, s[54:55]
	ds_read_b64 v[106:107], v213 offset:37120
	ds_read_b32 v182, v212 offset:17152
	v_add_f32_dpp v225, v224, v223 quad_perm:[2,3,0,1] row_mask:0xf bank_mask:0xf bound_ctrl:1
	ds_read_b128 v[76:79], v211 offset:16384
	ds_read_b128 v[174:177], v211 offset:17664
	v_add_f32_dpp v226, v225, v225 row_ror:4 row_mask:0xf bank_mask:0xf bound_ctrl:1
	ds_read_b64 v[154:155], v213 offset:37136
	ds_read_b32 v188, v212 offset:18176
	v_add_f32_dpp v210, v226, v226 row_ror:8 row_mask:0xf bank_mask:0xf bound_ctrl:1
	ds_read_b128 v[80:83], v211 offset:17408
	ds_write_b32 v214, v205 offset:32768
	ds_write_b32 v214, v208 offset:33024
	ds_write_b32 v214, v209 offset:33280
	ds_write_b32 v214, v210 offset:33536
	v_add_u32_e32 v211, 0x4000, v211
	v_add_u32_e32 v212, 0x4000, v212
	v_add_u32_e32 v213, 0x100, v213
	v_add_u32_e32 v214, 0x400, v214
	s_sub_i32 s50, s50, 1
	s_cmp_lg_u32 s50, 0
	s_cbranch_scc1 .Lscan0p_blk
